# split-K pairs made asymmetric (consumer 20 K-tiles, producer 12) and consumer loads the partial tile in two groups of 16 quads (on v74)
# baseline (speedup 1.0000x reference)
.LBB0_707:
	s_ashr_i32 s45, s44, 31
	s_lshl_b64 s[46:47], s[44:45], 20
	s_add_u32 s46, s80, s46
	s_addc_u32 s47, s81, s47
	s_cmp_eq_u32 s99, 2
	s_cselect_b32 s100, 0xa00, 0
	s_add_u32 s46, s46, s100
	s_addc_u32 s47, s47, 0
	s_and_b64 s[48:49], s[38:39], exec
	s_cselect_b32 s41, s47, s87
	s_cselect_b32 s45, s46, s86
	s_ashr_i32 s43, s42, 31
	s_lshl_b64 s[48:49], s[42:43], 20
	s_add_u32 s48, s56, s48
	s_addc_u32 s49, s55, s49
	s_add_u32 s48, s48, s100
	s_addc_u32 s49, s49, 0
	s_and_b64 s[64:65], s[38:39], exec
	s_cselect_b32 s43, s49, s9
	s_cselect_b32 s63, s48, s8
	s_add_u32 s86, s86, 0x80080
	s_addc_u32 s87, s87, 0
	s_add_u32 s64, s8, 0x100
	v_mov_b32_e32 v2, 0
	s_addc_u32 s65, s9, 0
	s_lshl_b32 s66, s98, 3
	s_add_i32 s66, s66, 2
	s_cmp_eq_u32 s98, 0
	s_cselect_b32 s66, -2, s66
	v_mov_b32_e32 v3, v2
	v_mov_b32_e32 v4, v2
	v_mov_b32_e32 v5, v2
	v_mov_b32_e32 v6, v2
	v_mov_b32_e32 v7, v2
	v_mov_b32_e32 v8, v2
	v_mov_b32_e32 v9, v2
	v_mov_b32_e32 v18, v2
	v_mov_b32_e32 v19, v2
	v_mov_b32_e32 v20, v2
	v_mov_b32_e32 v21, v2
	v_mov_b32_e32 v22, v2
	v_mov_b32_e32 v23, v2
	v_mov_b32_e32 v24, v2
	v_mov_b32_e32 v25, v2
	v_mov_b32_e32 v34, v2
	v_mov_b32_e32 v35, v2
	v_mov_b32_e32 v36, v2
	v_mov_b32_e32 v37, v2
	v_mov_b32_e32 v38, v2
	v_mov_b32_e32 v39, v2
	v_mov_b32_e32 v40, v2
	v_mov_b32_e32 v41, v2
	v_mov_b32_e32 v50, v2
	v_mov_b32_e32 v51, v2
	v_mov_b32_e32 v52, v2
	v_mov_b32_e32 v53, v2
	v_mov_b32_e32 v54, v2
	v_mov_b32_e32 v55, v2
	v_mov_b32_e32 v56, v2
	v_mov_b32_e32 v57, v2
	v_mov_b32_e32 v10, v2
	v_mov_b32_e32 v11, v2
	v_mov_b32_e32 v12, v2
	v_mov_b32_e32 v13, v2
	v_mov_b32_e32 v14, v2
	v_mov_b32_e32 v15, v2
	v_mov_b32_e32 v16, v2
	v_mov_b32_e32 v17, v2
	v_mov_b32_e32 v26, v2
	v_mov_b32_e32 v27, v2
	v_mov_b32_e32 v28, v2
	v_mov_b32_e32 v29, v2
	v_mov_b32_e32 v30, v2
	v_mov_b32_e32 v31, v2
	v_mov_b32_e32 v32, v2
	v_mov_b32_e32 v33, v2
	v_mov_b32_e32 v42, v2
	v_mov_b32_e32 v43, v2
	v_mov_b32_e32 v44, v2
	v_mov_b32_e32 v45, v2
	v_mov_b32_e32 v46, v2
	v_mov_b32_e32 v47, v2
	v_mov_b32_e32 v48, v2
	v_mov_b32_e32 v49, v2
	v_mov_b32_e32 v58, v2
	v_mov_b32_e32 v59, v2
	v_mov_b32_e32 v60, v2
	v_mov_b32_e32 v61, v2
	v_mov_b32_e32 v62, v2
	v_mov_b32_e32 v63, v2
	v_mov_b32_e32 v64, v2
	v_mov_b32_e32 v65, v2
	v_mov_b32_e32 v66, v2
	v_mov_b32_e32 v67, v2
	v_mov_b32_e32 v68, v2
	v_mov_b32_e32 v69, v2
	v_mov_b32_e32 v70, v2
	v_mov_b32_e32 v71, v2
	v_mov_b32_e32 v72, v2
	v_mov_b32_e32 v73, v2
	v_mov_b32_e32 v82, v2
	v_mov_b32_e32 v83, v2
	v_mov_b32_e32 v84, v2
	v_mov_b32_e32 v85, v2
	v_mov_b32_e32 v86, v2
	v_mov_b32_e32 v87, v2
	v_mov_b32_e32 v88, v2
	v_mov_b32_e32 v89, v2
	v_mov_b32_e32 v98, v2
	v_mov_b32_e32 v99, v2
	v_mov_b32_e32 v100, v2
	v_mov_b32_e32 v101, v2
	v_mov_b32_e32 v102, v2
	v_mov_b32_e32 v103, v2
	v_mov_b32_e32 v104, v2
	v_mov_b32_e32 v105, v2
	v_mov_b32_e32 v120, v2
	v_mov_b32_e32 v121, v2
	v_mov_b32_e32 v122, v2
	v_mov_b32_e32 v123, v2
	v_mov_b32_e32 v124, v2
	v_mov_b32_e32 v125, v2
	v_mov_b32_e32 v126, v2
	v_mov_b32_e32 v127, v2
	v_mov_b32_e32 v74, v2
	v_mov_b32_e32 v75, v2
	v_mov_b32_e32 v76, v2
	v_mov_b32_e32 v77, v2
	v_mov_b32_e32 v78, v2
	v_mov_b32_e32 v79, v2
	v_mov_b32_e32 v80, v2
	v_mov_b32_e32 v81, v2
	v_mov_b32_e32 v90, v2
	v_mov_b32_e32 v91, v2
	v_mov_b32_e32 v92, v2
	v_mov_b32_e32 v93, v2
	v_mov_b32_e32 v94, v2
	v_mov_b32_e32 v95, v2
	v_mov_b32_e32 v96, v2
	v_mov_b32_e32 v97, v2
	v_mov_b32_e32 v106, v2
	v_mov_b32_e32 v107, v2
	v_mov_b32_e32 v108, v2
	v_mov_b32_e32 v109, v2
	v_mov_b32_e32 v116, v2
	v_mov_b32_e32 v117, v2
	v_mov_b32_e32 v118, v2
	v_mov_b32_e32 v119, v2
	v_mov_b32_e32 v128, v2
	v_mov_b32_e32 v129, v2
	v_mov_b32_e32 v130, v2
	v_mov_b32_e32 v131, v2
	v_mov_b32_e32 v132, v2
	v_mov_b32_e32 v133, v2
	v_mov_b32_e32 v134, v2
	v_mov_b32_e32 v135, v2

.Lmy_sk_cgot2:
	s_or_b64 exec, exec, s[100:101]
	s_waitcnt vmcnt(0)
	s_barrier
	buffer_inv sc1
	s_lshr_b32 s100, s2, 1
	s_lshl_b32 s100, s100, 18
	s_add_u32 s100, s76, s100
	s_addc_u32 s101, s77, 0
	s_add_u32 s100, s100, 0x1a900000
	s_addc_u32 s101, s101, 0
	v_readfirstlane_b32 s99, v164
	s_lshr_b32 s99, s99, 6
	s_lshl_b32 s99, s99, 15
	s_add_u32 s100, s100, s99
	s_addc_u32 s101, s101, 0
	v_lshlrev_b32_e32 v250, 4, v202
	global_load_dwordx4 v[214:217], v250, s[100:101] sc0 sc1
	global_load_dwordx4 v[218:221], v250, s[100:101] offset:1024 sc0 sc1
	global_load_dwordx4 v[222:225], v250, s[100:101] offset:2048 sc0 sc1
	global_load_dwordx4 v[226:229], v250, s[100:101] offset:3072 sc0 sc1
	s_add_u32 s100, s100, 0x1000
	s_addc_u32 s101, s101, 0
	global_load_dwordx4 v[230:233], v250, s[100:101] sc0 sc1
	global_load_dwordx4 v[234:237], v250, s[100:101] offset:1024 sc0 sc1
	global_load_dwordx4 v[238:241], v250, s[100:101] offset:2048 sc0 sc1
	global_load_dwordx4 v[242:245], v250, s[100:101] offset:3072 sc0 sc1
	s_add_u32 s100, s100, 0x1000
	s_addc_u32 s101, s101, 0
	global_load_dwordx4 v[184:187], v250, s[100:101] sc0 sc1
	global_load_dwordx4 v[188:191], v250, s[100:101] offset:1024 sc0 sc1
	global_load_dwordx4 v[192:195], v250, s[100:101] offset:2048 sc0 sc1
	global_load_dwordx4 v[196:199], v250, s[100:101] offset:3072 sc0 sc1
	s_add_u32 s100, s100, 0x1000
	s_addc_u32 s101, s101, 0
	global_load_dwordx4 v[146:149], v250, s[100:101] sc0 sc1
	global_load_dwordx4 v[156:159], v250, s[100:101] offset:1024 sc0 sc1
	global_load_dwordx4 v[160:163], v250, s[100:101] offset:2048 sc0 sc1
	global_load_dwordx4 v[170:173], v250, s[100:101] offset:3072 sc0 sc1
	s_add_u32 s100, s100, 0x1000
	s_addc_u32 s101, s101, 0
	s_waitcnt vmcnt(15)
	v_pk_add_f32 v[132:133], v[132:133], v[214:215]
	v_pk_add_f32 v[134:135], v[134:135], v[216:217]
	s_waitcnt vmcnt(14)
	v_pk_add_f32 v[128:129], v[128:129], v[218:219]
	v_pk_add_f32 v[130:131], v[130:131], v[220:221]
	s_waitcnt vmcnt(13)
	v_pk_add_f32 v[116:117], v[116:117], v[222:223]
	v_pk_add_f32 v[118:119], v[118:119], v[224:225]
	s_waitcnt vmcnt(12)
	v_pk_add_f32 v[106:107], v[106:107], v[226:227]
	v_pk_add_f32 v[108:109], v[108:109], v[228:229]
	s_waitcnt vmcnt(11)
	v_pk_add_f32 v[94:95], v[94:95], v[230:231]
	v_pk_add_f32 v[96:97], v[96:97], v[232:233]
	s_waitcnt vmcnt(10)
	v_pk_add_f32 v[90:91], v[90:91], v[234:235]
	v_pk_add_f32 v[92:93], v[92:93], v[236:237]
	s_waitcnt vmcnt(9)
	v_pk_add_f32 v[78:79], v[78:79], v[238:239]
	v_pk_add_f32 v[80:81], v[80:81], v[240:241]
	s_waitcnt vmcnt(8)
	v_pk_add_f32 v[74:75], v[74:75], v[242:243]
	v_pk_add_f32 v[76:77], v[76:77], v[244:245]
	s_waitcnt vmcnt(7)
	v_pk_add_f32 v[124:125], v[124:125], v[184:185]
	v_pk_add_f32 v[126:127], v[126:127], v[186:187]
	s_waitcnt vmcnt(6)
	v_pk_add_f32 v[120:121], v[120:121], v[188:189]
	v_pk_add_f32 v[122:123], v[122:123], v[190:191]
	s_waitcnt vmcnt(5)
	v_pk_add_f32 v[102:103], v[102:103], v[192:193]
	v_pk_add_f32 v[104:105], v[104:105], v[194:195]
	s_waitcnt vmcnt(4)
	v_pk_add_f32 v[98:99], v[98:99], v[196:197]
	v_pk_add_f32 v[100:101], v[100:101], v[198:199]
	s_waitcnt vmcnt(3)
	v_pk_add_f32 v[86:87], v[86:87], v[146:147]
	v_pk_add_f32 v[88:89], v[88:89], v[148:149]
	s_waitcnt vmcnt(2)
	v_pk_add_f32 v[82:83], v[82:83], v[156:157]
	v_pk_add_f32 v[84:85], v[84:85], v[158:159]
	s_waitcnt vmcnt(1)
	v_pk_add_f32 v[70:71], v[70:71], v[160:161]
	v_pk_add_f32 v[72:73], v[72:73], v[162:163]
	s_waitcnt vmcnt(0)
	v_pk_add_f32 v[66:67], v[66:67], v[170:171]
	v_pk_add_f32 v[68:69], v[68:69], v[172:173]
	global_load_dwordx4 v[214:217], v250, s[100:101] sc0 sc1
	global_load_dwordx4 v[218:221], v250, s[100:101] offset:1024 sc0 sc1
	global_load_dwordx4 v[222:225], v250, s[100:101] offset:2048 sc0 sc1
	global_load_dwordx4 v[226:229], v250, s[100:101] offset:3072 sc0 sc1
	s_add_u32 s100, s100, 0x1000
	s_addc_u32 s101, s101, 0
	global_load_dwordx4 v[230:233], v250, s[100:101] sc0 sc1
	global_load_dwordx4 v[234:237], v250, s[100:101] offset:1024 sc0 sc1
	global_load_dwordx4 v[238:241], v250, s[100:101] offset:2048 sc0 sc1
	global_load_dwordx4 v[242:245], v250, s[100:101] offset:3072 sc0 sc1
	s_add_u32 s100, s100, 0x1000
	s_addc_u32 s101, s101, 0
	global_load_dwordx4 v[184:187], v250, s[100:101] sc0 sc1
	global_load_dwordx4 v[188:191], v250, s[100:101] offset:1024 sc0 sc1
	global_load_dwordx4 v[192:195], v250, s[100:101] offset:2048 sc0 sc1
	global_load_dwordx4 v[196:199], v250, s[100:101] offset:3072 sc0 sc1
	s_add_u32 s100, s100, 0x1000
	s_addc_u32 s101, s101, 0
	global_load_dwordx4 v[146:149], v250, s[100:101] sc0 sc1
	global_load_dwordx4 v[156:159], v250, s[100:101] offset:1024 sc0 sc1
	global_load_dwordx4 v[160:163], v250, s[100:101] offset:2048 sc0 sc1
	global_load_dwordx4 v[170:173], v250, s[100:101] offset:3072 sc0 sc1
	s_waitcnt vmcnt(15)
	v_pk_add_f32 v[62:63], v[62:63], v[214:215]
	v_pk_add_f32 v[64:65], v[64:65], v[216:217]
	s_waitcnt vmcnt(14)
	v_pk_add_f32 v[58:59], v[58:59], v[218:219]
	v_pk_add_f32 v[60:61], v[60:61], v[220:221]
	s_waitcnt vmcnt(13)
	v_pk_add_f32 v[46:47], v[46:47], v[222:223]
	v_pk_add_f32 v[48:49], v[48:49], v[224:225]
	s_waitcnt vmcnt(12)
	v_pk_add_f32 v[42:43], v[42:43], v[226:227]
	v_pk_add_f32 v[44:45], v[44:45], v[228:229]
	s_waitcnt vmcnt(11)
	v_pk_add_f32 v[30:31], v[30:31], v[230:231]
	v_pk_add_f32 v[32:33], v[32:33], v[232:233]
	s_waitcnt vmcnt(10)
	v_pk_add_f32 v[26:27], v[26:27], v[234:235]
	v_pk_add_f32 v[28:29], v[28:29], v[236:237]
	s_waitcnt vmcnt(9)
	v_pk_add_f32 v[14:15], v[14:15], v[238:239]
	v_pk_add_f32 v[16:17], v[16:17], v[240:241]
	s_waitcnt vmcnt(8)
	v_pk_add_f32 v[10:11], v[10:11], v[242:243]
	v_pk_add_f32 v[12:13], v[12:13], v[244:245]
	s_waitcnt vmcnt(7)
	v_pk_add_f32 v[54:55], v[54:55], v[184:185]
	v_pk_add_f32 v[56:57], v[56:57], v[186:187]
	s_waitcnt vmcnt(6)
	v_pk_add_f32 v[50:51], v[50:51], v[188:189]
	v_pk_add_f32 v[52:53], v[52:53], v[190:191]
	s_waitcnt vmcnt(5)
	v_pk_add_f32 v[38:39], v[38:39], v[192:193]
	v_pk_add_f32 v[40:41], v[40:41], v[194:195]
	s_waitcnt vmcnt(4)
	v_pk_add_f32 v[34:35], v[34:35], v[196:197]
	v_pk_add_f32 v[36:37], v[36:37], v[198:199]
	s_waitcnt vmcnt(3)
	v_pk_add_f32 v[22:23], v[22:23], v[146:147]
	v_pk_add_f32 v[24:25], v[24:25], v[148:149]
	s_waitcnt vmcnt(2)
	v_pk_add_f32 v[18:19], v[18:19], v[156:157]
	v_pk_add_f32 v[20:21], v[20:21], v[158:159]
	s_waitcnt vmcnt(1)
	v_pk_add_f32 v[6:7], v[6:7], v[160:161]
	v_pk_add_f32 v[8:9], v[8:9], v[162:163]
	s_waitcnt vmcnt(0)
	v_pk_add_f32 v[2:3], v[2:3], v[170:171]
	v_pk_add_f32 v[4:5], v[4:5], v[172:173]
	s_branch .Lmy_sk_norm
